# v60 plus lever 2 in the FF2 phase: the first two residual (X1) row groups requested at the phase start into spare registers and copied in the epilogue
# baseline (speedup 1.0000x reference)
.LBB0_640:
	s_or_b64 exec, exec, s[6:7]
	v_readlane_b32 s0, v242, 38
	v_readlane_b32 s1, v242, 39
	s_waitcnt lgkmcnt(0)
	s_barrier
	s_and_b64 vcc, exec, s[0:1]
	v_readfirstlane_b32 s34, v0
	s_and_b32 s98, s38, 7
	s_lshl_b32 s98, s98, 3
	s_lshr_b32 s99, s38, 5
	s_add_i32 s98, s98, s99
	s_mulk_i32 s98, 0xc0
	s_lshr_b32 s99, s34, 8
	s_mulk_i32 s99, 0x30
	s_add_i32 s98, s98, s99
	s_lshr_b32 s99, s38, 3
	s_and_b32 s99, s99, 3
	s_lshl_b32 s99, s99, 8
	s_lshr_b32 s100, s34, 6
	s_and_b32 s100, s100, 3
	s_lshl_b32 s100, s100, 5
	s_or_b32 s99, s99, s100
	v_lshrrev_b32_e32 v214, 1, v0
	v_and_or_b32 v214, v214, 24, s99
	v_lshlrev_b32_e32 v214, 1, v214
	v_mov_b32_e32 v215, 0
	v_and_b32_e32 v216, 15, v0
	v_or_b32_e32 v216, s98, v216
	v_mov_b32_e32 v217, 0
	v_lshlrev_b64 v[216:217], 11, v[216:217]
	v_lshl_add_u64 v[216:217], s[84:85], 0, v[216:217]
	v_lshl_add_u64 v[216:217], v[216:217], 0, v[214:215]
	s_mov_b32 s100, 0x8000
	s_mov_b32 s101, 0
	v_lshl_add_u64 v[214:215], s[100:101], 0, v[216:217]
	global_load_dwordx4 v[228:231], v[216:217], off
	global_load_dwordx4 v[232:235], v[216:217], off offset:256
	global_load_dwordx4 v[236:239], v[214:215], off
	global_load_dwordx4 v[210:213], v[214:215], off offset:256
	v_lshlrev_b32_e32 v1, 4, v0
	v_add_u32_e32 v2, 0x2000, v1
	v_ashrrev_i32_e32 v3, 31, v2
	v_lshrrev_b32_e32 v3, 22, v3
	v_add_u32_e32 v3, v2, v3
	v_ashrrev_i32_e32 v10, 10, v3
	v_mul_i32_i24_e32 v3, 0x400, v10
	v_sub_u32_e32 v2, v2, v3
	v_lshrrev_b32_e32 v3, 4, v2
	v_bitop3_b32 v2, v3, v2, 32 bitop3:0x6c
	v_ashrrev_i32_e32 v3, 31, v2
	v_lshrrev_b32_e32 v3, 26, v3
	v_add_u32_e32 v3, v2, v3
	v_lshlrev_b32_e32 v4, 3, v10
	v_ashrrev_i32_e32 v11, 6, v3
	v_and_b32_e32 v4, -16, v4
	v_add_u32_e32 v4, v11, v4
	v_and_b32_e32 v5, 3, v11
	s_mov_b32 s0, 0x7ffe0
	v_lshrrev_b32_e32 v6, 2, v4
	v_lshlrev_b32_e32 v7, 1, v4
	v_and_b32_e32 v3, 0xc0, v3
	v_and_or_b32 v5, v4, s0, v5
	v_and_b32_e32 v6, 4, v6
	v_and_b32_e32 v7, 24, v7
	v_sub_u32_e32 v2, v2, v3
	v_mov_b32_e32 v3, 1
	v_or3_b32 v5, v5, v6, v7
	v_lshlrev_b32_e32 v6, 5, v10
	v_ashrrev_i16_sdwa v2, v3, sext(v2) dst_sel:DWORD dst_unused:UNUSED_PAD src0_sel:DWORD src1_sel:BYTE_0
	v_and_b32_e32 v6, 32, v6
	v_bfe_i32 v12, v2, 0, 16
	v_add_lshl_u32 v2, v6, v12, 1
	v_lshl_add_u32 v122, v5, 13, v2
	v_lshl_add_u32 v124, v4, 13, v2
	v_add_u32_e32 v124, 0xfffe0000, v124
	v_bfe_i32 v2, v0, 27, 1
	v_lshrrev_b32_e32 v2, 22, v2
	v_add_u32_e32 v2, v1, v2
	v_and_b32_e32 v2, 0xfffffc00, v2
	v_sub_u32_e32 v1, v1, v2
	v_lshrrev_b32_e32 v2, 4, v1
	v_ashrrev_i32_e32 v4, 31, v0
	v_bitop3_b32 v1, v2, v1, 32 bitop3:0x6c
	v_lshrrev_b32_e32 v4, 26, v4
	v_ashrrev_i32_e32 v2, 31, v1
	v_add_u32_e32 v4, v0, v4
	v_lshrrev_b32_e32 v2, 26, v2
	v_ashrrev_i32_e32 v14, 6, v4
	v_add_u32_e32 v2, v1, v2
	v_lshlrev_b32_e32 v4, 3, v14
	v_ashrrev_i32_e32 v13, 6, v2
	v_and_b32_e32 v4, -16, v4
	v_add_u32_e32 v4, v13, v4
	v_and_b32_e32 v5, 3, v13
	s_ashr_i32 s36, s38, 31
	v_and_or_b32 v5, v4, s0, v5
	s_lshr_b32 s0, s36, 29
	s_add_i32 s0, s38, s0
	s_ashr_i32 s3, s34, 6
	s_ashr_i32 s1, s0, 3
	s_and_b32 s0, s0, -8
	s_ashr_i32 s11, s34, 8
	s_lshl_b32 s35, s3, 10
	s_sub_i32 s0, s38, s0
	s_cmp_lt_i32 s0, 0
	s_cselect_b32 s4, 25, 24
	s_mul_i32 s0, s0, s4
	s_add_i32 s0, s0, s1
	s_mul_hi_i32 s1, s0, 0x2aaaaaab
	s_lshr_b32 s4, s1, 31
	s_ashr_i32 s1, s1, 2
	s_add_i32 s1, s1, s4
	s_mul_i32 s4, s1, 6
	s_mul_i32 s1, s1, 24
	s_sub_i32 s1, s0, s1
	s_mul_i32 s0, s1, 43
	s_bfe_u32 s5, s0, 0x1000f
	s_bfe_u32 s0, s0, 0x80008
	s_add_i32 s0, s0, s5
	s_mul_i32 s5, s0, 6
	s_sub_i32 s1, s1, s5
	s_sext_i32_i8 s1, s1
	v_lshrrev_b32_e32 v6, 2, v4
	v_lshlrev_b32_e32 v7, 1, v4
	v_and_b32_e32 v2, 0xc0, v2
	s_add_i32 s6, s4, s1
	v_and_b32_e32 v6, 4, v6
	v_and_b32_e32 v7, 24, v7
	v_sub_u32_e32 v1, v1, v2
	s_lshr_b32 s1, s38, 3
	s_and_b32 s0, s1, 3
	s_lshr_b32 s1, s1, 2
	s_and_b32 s6, s38, 7
	s_lshl_b32 s6, s6, 3
	s_add_i32 s6, s6, s1
	s_ashr_i32 s7, s6, 31
	s_bfe_i64 s[14:15], s[0:1], 0x80000
	v_or3_b32 v5, v5, v6, v7
	v_lshlrev_b32_e32 v6, 5, v14
	v_ashrrev_i16_sdwa v1, v3, sext(v1) dst_sel:DWORD dst_unused:UNUSED_PAD src0_sel:DWORD src1_sel:BYTE_0
	s_mul_i32 s4, s6, 0x180000
	s_mov_b32 s5, 0
	s_lshl_b64 s[14:15], s[14:15], 21
	v_and_b32_e32 v6, 32, v6
	v_bfe_i32 v15, v1, 0, 16
	s_add_u32 s26, s86, s14
	v_add_lshl_u32 v1, v6, v15, 1
	s_addc_u32 s27, s87, s15
	s_add_i32 s37, s35, 0
	v_lshl_add_u32 v134, v5, 13, v1
	s_add_i32 m0, s37, 0x10000
	v_lshl_add_u32 v136, v4, 13, v1
	global_load_lds_dwordx4 v134, s[26:27]
	s_add_i32 m0, s37, 0x12000
	s_add_u32 s14, s26, 0x100000
	global_load_lds_dwordx4 v122, s[26:27]
	s_addc_u32 s15, s27, 0
	s_add_i32 m0, s37, 0x14000
	v_mov_b32_e32 v135, 0
	global_load_lds_dwordx4 v134, s[14:15]
	s_add_i32 m0, s37, 0x16000
	v_mov_b32_e32 v123, v135
	global_load_lds_dwordx4 v122, s[14:15]
	s_add_u32 s14, s68, s4
	s_addc_u32 s15, s69, s5
	s_add_i32 s41, s37, 0x2000
	s_mov_b32 m0, s37
	s_add_u32 s4, s14, 0xc0000
	global_load_lds_dwordx4 v136, s[14:15]
	s_mov_b32 m0, s41
	s_addc_u32 s5, s15, 0
	s_add_i32 s42, s37, 0x4000
	global_load_lds_dwordx4 v124, s[14:15]
	s_mov_b32 m0, s42
	s_add_i32 s43, s37, 0x6000
	global_load_lds_dwordx4 v136, s[4:5]
	s_mov_b32 m0, s43
	v_mov_b32_e32 v137, v135
	global_load_lds_dwordx4 v124, s[4:5]
	v_mov_b32_e32 v125, v135
	s_mov_b32 s44, 0
	v_lshl_add_u64 v[8:9], s[26:27], 0, v[134:135]
	v_lshl_add_u64 v[6:7], s[26:27], 0, v[122:123]
	v_lshl_add_u64 v[4:5], s[14:15], 0, v[136:137]
	s_cmp_lg_u32 s11, 1
	v_lshl_add_u64 v[2:3], s[14:15], 0, v[124:125]
	s_cbranch_scc1 .LBB0_643
	s_barrier

.Lp9_nostraddle:
	s_lshr_b32 s99, s40, 2
	s_sub_i32 s99, s98, s99
	s_mov_b32 s1, 0
	s_lshl_b64 s[0:1], s[0:1], 2
	v_readlane_b32 s4, v242, 34
	v_readlane_b32 s5, v242, 35
	s_add_u32 s0, s4, s0
	s_addc_u32 s1, s5, s1
	s_lshl_b32 s18, s6, 8
	v_ashrrev_i32_e32 v123, 31, v122
	s_add_i32 s2, s99, s40
	v_lshlrev_b64 v[166:167], 2, v[122:123]
	v_or_b32_e32 v168, s2, v1
	v_lshl_add_u64 v[124:125], s[46:47], 0, v[166:167]
	v_ashrrev_i32_e32 v169, 31, v168
	s_barrier
	global_load_dwordx4 v[146:149], v[124:125], off offset:16
	global_load_dwordx4 v[154:157], v[124:125], off
	global_load_dwordx4 v[134:137], v[124:125], off offset:528
	global_load_dwordx4 v[138:141], v[124:125], off offset:512
	v_lshlrev_b64 v[124:125], 11, v[168:169]
	v_lshl_add_u64 v[124:125], s[84:85], 0, v[124:125]
	v_lshlrev_b64 v[170:171], 1, v[122:123]
	v_lshl_add_u64 v[142:143], v[124:125], 0, v[170:171]
	v_lshl_add_u64 v[142:143], s[0:1], 0, v[166:167]
	s_movk_i32 s2, 0x5000
	v_add_u32_e32 v178, 16, v168
	s_mov_b64 s[0:1], 0x5000
	v_add_co_u32_e32 v144, vcc, s2, v142
	v_ashrrev_i32_e32 v179, 31, v178
	s_nop 0
	v_addc_co_u32_e32 v145, vcc, 0, v143, vcc
	v_add_co_u32_e32 v240, vcc, 0xb000, v142
	s_nop 1
	v_addc_co_u32_e32 v241, vcc, 0, v143, vcc
	v_lshl_add_u64 v[142:143], v[142:143], 0, s[0:1]
	v_lshlrev_b64 v[178:179], 11, v[178:179]
	global_load_dwordx4 v[162:165], v[144:145], off
	global_load_dwordx4 v[158:161], v[142:143], off offset:16
	global_load_dwordx4 v[150:153], v[142:143], off offset:512
	s_nop 0
	global_load_dwordx4 v[142:145], v[142:143], off offset:528
	v_lshl_add_u64 v[178:179], s[84:85], 0, v[178:179]
	v_lshl_add_u64 v[182:183], v[178:179], 0, v[170:171]
	s_nop 0
	v_add_u32_e32 v186, 32, v168
	v_ashrrev_i32_e32 v187, 31, v186
	s_mov_b32 s0, 0x3f9837f0
	v_lshlrev_b64 v[186:187], 11, v[186:187]
	v_lshl_add_u64 v[186:187], s[84:85], 0, v[186:187]
	s_waitcnt vmcnt(0)
	v_mov_b32_e32 v122, v228
	v_mov_b32_e32 v123, v229
	v_mov_b32_e32 v124, v230
	v_mov_b32_e32 v125, v231
	v_mov_b32_e32 v174, v232
	v_mov_b32_e32 v175, v233
	v_mov_b32_e32 v176, v234
	v_mov_b32_e32 v177, v235
	v_mov_b32_e32 v178, v236
	v_mov_b32_e32 v179, v237
	v_mov_b32_e32 v180, v238
	v_mov_b32_e32 v181, v239
	v_mov_b32_e32 v182, v210
	v_mov_b32_e32 v183, v211
	v_mov_b32_e32 v184, v212
	v_mov_b32_e32 v185, v213
	v_pk_add_f32 v[108:109], v[108:109], v[148:149]
	v_pk_add_f32 v[116:117], v[116:117], v[156:157]
	v_pk_add_f32 v[114:115], v[114:115], v[154:155]
	v_pk_add_f32 v[106:107], v[106:107], v[146:147]
	v_pk_add_f32 v[100:101], v[100:101], v[140:141]
	v_pk_add_f32 v[98:99], v[98:99], v[138:139]
	v_pk_add_f32 v[84:85], v[84:85], v[136:137]
	v_lshlrev_b32_e32 v188, 16, v122
	v_and_b32_e32 v189, 0xffff0000, v122
	v_lshlrev_b32_e32 v122, 16, v123
	v_and_b32_e32 v123, 0xffff0000, v123
	v_lshlrev_b32_e32 v190, 16, v124
	v_and_b32_e32 v191, 0xffff0000, v124
	v_lshlrev_b32_e32 v124, 16, v125
	v_and_b32_e32 v125, 0xffff0000, v125
	v_lshlrev_b32_e32 v192, 16, v174
	v_and_b32_e32 v193, 0xffff0000, v174
	v_lshlrev_b32_e32 v174, 16, v175
	v_and_b32_e32 v175, 0xffff0000, v175
	v_lshlrev_b32_e32 v194, 16, v176
	v_and_b32_e32 v195, 0xffff0000, v176
	v_lshlrev_b32_e32 v176, 16, v177
	v_and_b32_e32 v177, 0xffff0000, v177
	v_pk_add_f32 v[82:83], v[82:83], v[134:135]
	v_pk_mul_f32 v[196:197], v[122:123], s[0:1] op_sel_hi:[1,0]
	v_pk_mul_f32 v[122:123], v[188:189], s[0:1] op_sel_hi:[1,0]
	v_pk_mul_f32 v[188:189], v[190:191], s[0:1] op_sel_hi:[1,0]
	v_pk_mul_f32 v[190:191], v[124:125], s[0:1] op_sel_hi:[1,0]
	v_pk_mul_f32 v[192:193], v[192:193], s[0:1] op_sel_hi:[1,0]
	v_pk_mul_f32 v[174:175], v[174:175], s[0:1] op_sel_hi:[1,0]
	v_pk_mul_f32 v[194:195], v[194:195], s[0:1] op_sel_hi:[1,0]
	v_pk_mul_f32 v[176:177], v[176:177], s[0:1] op_sel_hi:[1,0]
	v_pk_fma_f32 v[122:123], v[162:163], v[114:115], v[122:123]
	v_pk_fma_f32 v[124:125], v[164:165], v[116:117], v[196:197]
	v_pk_fma_f32 v[116:117], v[160:161], v[108:109], v[190:191]
	v_pk_fma_f32 v[114:115], v[158:159], v[106:107], v[188:189]
	v_pk_fma_f32 v[108:109], v[152:153], v[100:101], v[174:175]
	v_pk_fma_f32 v[106:107], v[150:151], v[98:99], v[192:193]
	v_pk_fma_f32 v[100:101], v[144:145], v[84:85], v[176:177]
	v_pk_fma_f32 v[98:99], v[142:143], v[82:83], v[194:195]
	v_lshl_add_u64 v[82:83], v[186:187], 0, v[170:171]
	s_cmp_eq_u32 s100, 1
	s_cbranch_scc0 .Lp9_gate_1
	global_load_dwordx4 v[162:165], v[240:241], off
	global_load_dwordx4 v[158:161], v[240:241], off offset:16
	global_load_dwordx4 v[150:153], v[240:241], off offset:512
	global_load_dwordx4 v[142:145], v[240:241], off offset:528
	s_waitcnt vmcnt(0)
